# group barriers: returning arrive atomic (last arriver skips polling); conversion stores no longer drained inside seams except the last one; one done-bump per workgroup after seam 8
# speedup vs baseline: 1.0163x; 1.0022x over previous
.LBB0_303:
	v_readlane_b32 s0, v254, 0
	v_readlane_b32 s1, v254, 1
	s_cmp_gt_i32 s1, 3
	s_cselect_b64 s[0:1], -1, 0
	s_and_b64 s[4:5], s[4:5], s[0:1]
	s_andn2_b64 vcc, exec, s[4:5]
	s_cbranch_vccnz .LBB0_357
	s_waitcnt vmcnt(0)
	s_waitcnt vmcnt(0) lgkmcnt(0)
	s_barrier
	s_mov_b64 s[4:5], exec
	v_readlane_b32 s6, v254, 7
	v_readlane_b32 s7, v254, 8
	s_and_b64 s[6:7], s[4:5], s[6:7]
	s_mov_b64 exec, s[6:7]
	s_cbranch_execz .Lmy_cv2_entry
	s_cmpk_lg_i32 s3, 0x100
	s_cbranch_scc1 .Lmy_gb2_orig
	s_and_b32 s6, s2, 7
	s_lshl_b32 s6, s6, 6
	s_add_u32 s6, s6, 0x33800
	v_mov_b32_e32 v2, s6
	v_mov_b32_e32 v3, 1
	global_atomic_add v4, v2, v3, s[50:51] sc0
	s_movk_i32 s7, 0x4000
	s_waitcnt vmcnt(0)
	v_cmp_gt_u32_e32 vcc, 31, v4
	s_cbranch_vccz .Lmy_gb2_go

.Lmy_cv2_go:
	s_add_u32 s20, s50, s20
	s_addc_u32 s21, s51, 0
	v_and_b32_e32 v2, 7, v1
	v_lshrrev_b32_e32 v3, 3, v1
	s_lshl_b32 s24, s15, 6
	v_lshl_add_u32 v4, v2, 3, s24
	v_mul_lo_u32 v4, v4, s19
	v_lshl_add_u32 v5, v3, 2, s17
	v_add_u32_e32 v4, v4, v5
	v_mov_b32_e32 v5, 0
	v_lshlrev_b64 v[4:5], 2, v[4:5]
	s_lshl_b32 s26, s19, 2
	s_mov_b32 s27, 0
	s_lshr_b32 s28, s18, 8
	s_and_b32 s29, s18, 0xff
	s_lshl_b32 s28, s28, 5
	s_add_u32 s28, s28, s15
	s_lshl_b32 s28, s28, 8
	s_add_u32 s28, s28, s29
	s_waitcnt lgkmcnt(0)
	v_lshl_add_u64 v[4:5], s[12:13], 0, v[4:5]
	global_load_dwordx4 v[8:11], v[4:5], off nt
	v_lshl_add_u64 v[4:5], v[4:5], 0, s[26:27]
	global_load_dwordx4 v[12:15], v[4:5], off nt
	v_lshl_add_u64 v[4:5], v[4:5], 0, s[26:27]
	global_load_dwordx4 v[16:19], v[4:5], off nt
	v_lshl_add_u64 v[4:5], v[4:5], 0, s[26:27]
	global_load_dwordx4 v[20:23], v[4:5], off nt
	v_lshl_add_u64 v[4:5], v[4:5], 0, s[26:27]
	global_load_dwordx4 v[24:27], v[4:5], off nt
	v_lshl_add_u64 v[4:5], v[4:5], 0, s[26:27]
	global_load_dwordx4 v[28:31], v[4:5], off nt
	v_lshl_add_u64 v[4:5], v[4:5], 0, s[26:27]
	global_load_dwordx4 v[32:35], v[4:5], off nt
	v_lshl_add_u64 v[4:5], v[4:5], 0, s[26:27]
	global_load_dwordx4 v[36:39], v[4:5], off nt
	v_lshl_add_u32 v6, v3, 2, s28
	v_lshlrev_b32_e32 v6, 7, v6
	v_lshl_add_u32 v6, v2, 4, v6
	v_mov_b32_e32 v7, 0
	v_lshl_add_u64 v[6:7], s[20:21], 0, v[6:7]
	s_waitcnt vmcnt(0)
	v_cvt_pk_bf16_f32 v40, v8, v12
	v_cvt_pk_bf16_f32 v41, v16, v20
	v_cvt_pk_bf16_f32 v42, v24, v28
	v_cvt_pk_bf16_f32 v43, v32, v36
	global_store_dwordx4 v[6:7], v[40:43], off sc1
	v_cvt_pk_bf16_f32 v44, v9, v13
	v_cvt_pk_bf16_f32 v45, v17, v21
	v_cvt_pk_bf16_f32 v46, v25, v29
	v_cvt_pk_bf16_f32 v47, v33, v37
	global_store_dwordx4 v[6:7], v[44:47], off offset:128 sc1
	v_cvt_pk_bf16_f32 v48, v10, v14
	v_cvt_pk_bf16_f32 v49, v18, v22
	v_cvt_pk_bf16_f32 v50, v26, v30
	v_cvt_pk_bf16_f32 v51, v34, v38
	global_store_dwordx4 v[6:7], v[48:51], off offset:256 sc1
	v_cvt_pk_bf16_f32 v52, v11, v15
	v_cvt_pk_bf16_f32 v53, v19, v23
	v_cvt_pk_bf16_f32 v54, v27, v31
	v_cvt_pk_bf16_f32 v55, v35, v39
	global_store_dwordx4 v[6:7], v[52:55], off offset:384 sc1
.Lmy_cv2_done:
	s_branch .LBB0_356

.LBB0_382:
	v_readlane_b32 s0, v254, 0
	v_readlane_b32 s1, v254, 1
	s_cmp_gt_i32 s1, 4
	s_cselect_b64 s[0:1], -1, 0
	s_and_b64 s[4:5], s[6:7], s[0:1]
	s_andn2_b64 vcc, exec, s[4:5]
	s_cbranch_vccnz .LBB0_436
	s_waitcnt vmcnt(0)
	s_waitcnt vmcnt(0) lgkmcnt(0)
	s_barrier
	s_mov_b64 s[4:5], exec
	v_readlane_b32 s6, v254, 7
	v_readlane_b32 s7, v254, 8
	s_and_b64 s[6:7], s[4:5], s[6:7]
	s_mov_b64 exec, s[6:7]
	s_cbranch_execz .Lmy_cv3_entry
	s_cmpk_lg_i32 s3, 0x100
	s_cbranch_scc1 .Lmy_gb3_orig
	s_and_b32 s6, s2, 7
	s_lshl_b32 s6, s6, 6
	s_add_u32 s6, s6, 0x33a00
	v_mov_b32_e32 v2, s6
	v_mov_b32_e32 v3, 1
	global_atomic_add v4, v2, v3, s[50:51] sc0
	s_movk_i32 s7, 0x4000
	s_waitcnt vmcnt(0)
	v_cmp_gt_u32_e32 vcc, 31, v4
	s_cbranch_vccz .Lmy_gb3_go

.Lmy_cv3_go:
	s_add_u32 s20, s50, s20
	s_addc_u32 s21, s51, 0
	v_and_b32_e32 v2, 7, v1
	v_lshrrev_b32_e32 v3, 3, v1
	s_lshl_b32 s24, s15, 6
	v_lshl_add_u32 v4, v2, 3, s24
	v_mul_lo_u32 v4, v4, s19
	v_lshl_add_u32 v5, v3, 2, s17
	v_add_u32_e32 v4, v4, v5
	v_mov_b32_e32 v5, 0
	v_lshlrev_b64 v[4:5], 2, v[4:5]
	s_lshl_b32 s26, s19, 2
	s_mov_b32 s27, 0
	s_lshr_b32 s28, s18, 8
	s_and_b32 s29, s18, 0xff
	s_lshl_b32 s28, s28, 5
	s_add_u32 s28, s28, s15
	s_lshl_b32 s28, s28, 8
	s_add_u32 s28, s28, s29
	s_waitcnt lgkmcnt(0)
	v_lshl_add_u64 v[4:5], s[12:13], 0, v[4:5]
	global_load_dwordx4 v[8:11], v[4:5], off nt
	v_lshl_add_u64 v[4:5], v[4:5], 0, s[26:27]
	global_load_dwordx4 v[12:15], v[4:5], off nt
	v_lshl_add_u64 v[4:5], v[4:5], 0, s[26:27]
	global_load_dwordx4 v[16:19], v[4:5], off nt
	v_lshl_add_u64 v[4:5], v[4:5], 0, s[26:27]
	global_load_dwordx4 v[20:23], v[4:5], off nt
	v_lshl_add_u64 v[4:5], v[4:5], 0, s[26:27]
	global_load_dwordx4 v[24:27], v[4:5], off nt
	v_lshl_add_u64 v[4:5], v[4:5], 0, s[26:27]
	global_load_dwordx4 v[28:31], v[4:5], off nt
	v_lshl_add_u64 v[4:5], v[4:5], 0, s[26:27]
	global_load_dwordx4 v[32:35], v[4:5], off nt
	v_lshl_add_u64 v[4:5], v[4:5], 0, s[26:27]
	global_load_dwordx4 v[36:39], v[4:5], off nt
	v_lshl_add_u32 v6, v3, 2, s28
	v_lshlrev_b32_e32 v6, 7, v6
	v_lshl_add_u32 v6, v2, 4, v6
	v_mov_b32_e32 v7, 0
	v_lshl_add_u64 v[6:7], s[20:21], 0, v[6:7]
	s_waitcnt vmcnt(0)
	v_cvt_pk_bf16_f32 v40, v8, v12
	v_cvt_pk_bf16_f32 v41, v16, v20
	v_cvt_pk_bf16_f32 v42, v24, v28
	v_cvt_pk_bf16_f32 v43, v32, v36
	global_store_dwordx4 v[6:7], v[40:43], off sc1
	v_cvt_pk_bf16_f32 v44, v9, v13
	v_cvt_pk_bf16_f32 v45, v17, v21
	v_cvt_pk_bf16_f32 v46, v25, v29
	v_cvt_pk_bf16_f32 v47, v33, v37
	global_store_dwordx4 v[6:7], v[44:47], off offset:128 sc1
	v_cvt_pk_bf16_f32 v48, v10, v14
	v_cvt_pk_bf16_f32 v49, v18, v22
	v_cvt_pk_bf16_f32 v50, v26, v30
	v_cvt_pk_bf16_f32 v51, v34, v38
	global_store_dwordx4 v[6:7], v[48:51], off offset:256 sc1
	v_cvt_pk_bf16_f32 v52, v11, v15
	v_cvt_pk_bf16_f32 v53, v19, v23
	v_cvt_pk_bf16_f32 v54, v27, v31
	v_cvt_pk_bf16_f32 v55, v35, v39
	global_store_dwordx4 v[6:7], v[52:55], off offset:384 sc1
.Lmy_cv3_done:
	s_branch .LBB0_435

.LBB0_440:
	v_readlane_b32 s0, v254, 0
	v_readlane_b32 s1, v254, 1
	s_cmp_gt_i32 s1, 5
	s_cselect_b64 s[0:1], -1, 0
	s_and_b64 s[4:5], s[4:5], s[0:1]
	s_andn2_b64 vcc, exec, s[4:5]
	s_cbranch_vccnz .LBB0_494
	s_waitcnt vmcnt(0)
	s_waitcnt vmcnt(0) lgkmcnt(0)
	s_barrier
	s_mov_b64 s[4:5], exec
	v_readlane_b32 s6, v254, 7
	v_readlane_b32 s7, v254, 8
	s_and_b64 s[6:7], s[4:5], s[6:7]
	s_mov_b64 exec, s[6:7]
	s_cbranch_execz .Lmy_cv4_entry
	s_cmpk_lg_i32 s3, 0x100
	s_cbranch_scc1 .Lmy_gb4_orig
	s_and_b32 s6, s2, 7
	s_lshl_b32 s6, s6, 6
	s_add_u32 s6, s6, 0x33c00
	v_mov_b32_e32 v2, s6
	v_mov_b32_e32 v3, 1
	global_atomic_add v4, v2, v3, s[50:51] sc0
	s_movk_i32 s7, 0x4000
	s_waitcnt vmcnt(0)
	v_cmp_gt_u32_e32 vcc, 31, v4
	s_cbranch_vccz .Lmy_gb4_go

.Lmy_cv4_go:
	s_add_u32 s20, s50, s20
	s_addc_u32 s21, s51, 0
	v_and_b32_e32 v2, 7, v1
	v_lshrrev_b32_e32 v3, 3, v1
	s_lshl_b32 s24, s15, 6
	v_lshl_add_u32 v4, v2, 3, s24
	v_mul_lo_u32 v4, v4, s19
	v_lshl_add_u32 v5, v3, 2, s17
	v_add_u32_e32 v4, v4, v5
	v_mov_b32_e32 v5, 0
	v_lshlrev_b64 v[4:5], 2, v[4:5]
	s_lshl_b32 s26, s19, 2
	s_mov_b32 s27, 0
	s_lshr_b32 s28, s18, 8
	s_and_b32 s29, s18, 0xff
	s_lshl_b32 s28, s28, 5
	s_add_u32 s28, s28, s15
	s_lshl_b32 s28, s28, 8
	s_add_u32 s28, s28, s29
	s_waitcnt lgkmcnt(0)
	v_lshl_add_u64 v[4:5], s[12:13], 0, v[4:5]
	global_load_dwordx4 v[8:11], v[4:5], off nt
	v_lshl_add_u64 v[4:5], v[4:5], 0, s[26:27]
	global_load_dwordx4 v[12:15], v[4:5], off nt
	v_lshl_add_u64 v[4:5], v[4:5], 0, s[26:27]
	global_load_dwordx4 v[16:19], v[4:5], off nt
	v_lshl_add_u64 v[4:5], v[4:5], 0, s[26:27]
	global_load_dwordx4 v[20:23], v[4:5], off nt
	v_lshl_add_u64 v[4:5], v[4:5], 0, s[26:27]
	global_load_dwordx4 v[24:27], v[4:5], off nt
	v_lshl_add_u64 v[4:5], v[4:5], 0, s[26:27]
	global_load_dwordx4 v[28:31], v[4:5], off nt
	v_lshl_add_u64 v[4:5], v[4:5], 0, s[26:27]
	global_load_dwordx4 v[32:35], v[4:5], off nt
	v_lshl_add_u64 v[4:5], v[4:5], 0, s[26:27]
	global_load_dwordx4 v[36:39], v[4:5], off nt
	v_lshl_add_u32 v6, v3, 2, s28
	v_lshlrev_b32_e32 v6, 7, v6
	v_lshl_add_u32 v6, v2, 4, v6
	v_mov_b32_e32 v7, 0
	v_lshl_add_u64 v[6:7], s[20:21], 0, v[6:7]
	s_waitcnt vmcnt(0)
	v_cvt_pk_bf16_f32 v40, v8, v12
	v_cvt_pk_bf16_f32 v41, v16, v20
	v_cvt_pk_bf16_f32 v42, v24, v28
	v_cvt_pk_bf16_f32 v43, v32, v36
	global_store_dwordx4 v[6:7], v[40:43], off sc1
	v_cvt_pk_bf16_f32 v44, v9, v13
	v_cvt_pk_bf16_f32 v45, v17, v21
	v_cvt_pk_bf16_f32 v46, v25, v29
	v_cvt_pk_bf16_f32 v47, v33, v37
	global_store_dwordx4 v[6:7], v[44:47], off offset:128 sc1
	v_cvt_pk_bf16_f32 v48, v10, v14
	v_cvt_pk_bf16_f32 v49, v18, v22
	v_cvt_pk_bf16_f32 v50, v26, v30
	v_cvt_pk_bf16_f32 v51, v34, v38
	global_store_dwordx4 v[6:7], v[48:51], off offset:256 sc1
	v_cvt_pk_bf16_f32 v52, v11, v15
	v_cvt_pk_bf16_f32 v53, v19, v23
	v_cvt_pk_bf16_f32 v54, v27, v31
	v_cvt_pk_bf16_f32 v55, v35, v39
	global_store_dwordx4 v[6:7], v[52:55], off offset:384 sc1
.Lmy_cv4_done:
	s_branch .LBB0_493

.Lmy_cv5_go:
	s_add_u32 s20, s50, s20
	s_addc_u32 s21, s51, 0
	v_and_b32_e32 v2, 7, v1
	v_lshrrev_b32_e32 v3, 3, v1
	s_lshl_b32 s24, s15, 6
	v_lshl_add_u32 v4, v2, 3, s24
	v_mul_lo_u32 v4, v4, s19
	v_lshl_add_u32 v5, v3, 2, s17
	v_add_u32_e32 v4, v4, v5
	v_mov_b32_e32 v5, 0
	v_lshlrev_b64 v[4:5], 2, v[4:5]
	s_lshl_b32 s26, s19, 2
	s_mov_b32 s27, 0
	s_lshr_b32 s28, s18, 8
	s_and_b32 s29, s18, 0xff
	s_lshl_b32 s28, s28, 5
	s_add_u32 s28, s28, s15
	s_lshl_b32 s28, s28, 8
	s_add_u32 s28, s28, s29
	s_waitcnt lgkmcnt(0)
	v_lshl_add_u64 v[4:5], s[12:13], 0, v[4:5]
	global_load_dwordx4 v[8:11], v[4:5], off nt
	v_lshl_add_u64 v[4:5], v[4:5], 0, s[26:27]
	global_load_dwordx4 v[12:15], v[4:5], off nt
	v_lshl_add_u64 v[4:5], v[4:5], 0, s[26:27]
	global_load_dwordx4 v[16:19], v[4:5], off nt
	v_lshl_add_u64 v[4:5], v[4:5], 0, s[26:27]
	global_load_dwordx4 v[20:23], v[4:5], off nt
	v_lshl_add_u64 v[4:5], v[4:5], 0, s[26:27]
	global_load_dwordx4 v[24:27], v[4:5], off nt
	v_lshl_add_u64 v[4:5], v[4:5], 0, s[26:27]
	global_load_dwordx4 v[28:31], v[4:5], off nt
	v_lshl_add_u64 v[4:5], v[4:5], 0, s[26:27]
	global_load_dwordx4 v[32:35], v[4:5], off nt
	v_lshl_add_u64 v[4:5], v[4:5], 0, s[26:27]
	global_load_dwordx4 v[36:39], v[4:5], off nt
	v_lshl_add_u32 v6, v3, 2, s28
	v_lshlrev_b32_e32 v6, 7, v6
	v_lshl_add_u32 v6, v2, 4, v6
	v_mov_b32_e32 v7, 0
	v_lshl_add_u64 v[6:7], s[20:21], 0, v[6:7]
	s_waitcnt vmcnt(0)
	v_cvt_pk_bf16_f32 v40, v8, v12
	v_cvt_pk_bf16_f32 v41, v16, v20
	v_cvt_pk_bf16_f32 v42, v24, v28
	v_cvt_pk_bf16_f32 v43, v32, v36
	global_store_dwordx4 v[6:7], v[40:43], off sc1
	v_cvt_pk_bf16_f32 v44, v9, v13
	v_cvt_pk_bf16_f32 v45, v17, v21
	v_cvt_pk_bf16_f32 v46, v25, v29
	v_cvt_pk_bf16_f32 v47, v33, v37
	global_store_dwordx4 v[6:7], v[44:47], off offset:128 sc1
	v_cvt_pk_bf16_f32 v48, v10, v14
	v_cvt_pk_bf16_f32 v49, v18, v22
	v_cvt_pk_bf16_f32 v50, v26, v30
	v_cvt_pk_bf16_f32 v51, v34, v38
	global_store_dwordx4 v[6:7], v[48:51], off offset:256 sc1
	v_cvt_pk_bf16_f32 v52, v11, v15
	v_cvt_pk_bf16_f32 v53, v19, v23
	v_cvt_pk_bf16_f32 v54, v27, v31
	v_cvt_pk_bf16_f32 v55, v35, v39
	global_store_dwordx4 v[6:7], v[52:55], off offset:384 sc1
.Lmy_cv5_done:
	s_branch .LBB0_626

.Lmy_cv6_go:
	s_add_u32 s20, s50, s20
	s_addc_u32 s21, s51, 0
	v_and_b32_e32 v2, 7, v1
	v_lshrrev_b32_e32 v3, 3, v1
	s_lshl_b32 s24, s15, 6
	v_lshl_add_u32 v4, v2, 3, s24
	v_mul_lo_u32 v4, v4, s19
	v_lshl_add_u32 v5, v3, 2, s17
	v_add_u32_e32 v4, v4, v5
	v_mov_b32_e32 v5, 0
	v_lshlrev_b64 v[4:5], 2, v[4:5]
	s_lshl_b32 s26, s19, 2
	s_mov_b32 s27, 0
	s_lshr_b32 s28, s18, 8
	s_and_b32 s29, s18, 0xff
	s_lshl_b32 s28, s28, 5
	s_add_u32 s28, s28, s15
	s_lshl_b32 s28, s28, 8
	s_add_u32 s28, s28, s29
	s_waitcnt lgkmcnt(0)
	v_lshl_add_u64 v[4:5], s[12:13], 0, v[4:5]
	global_load_dwordx4 v[8:11], v[4:5], off nt
	v_lshl_add_u64 v[4:5], v[4:5], 0, s[26:27]
	global_load_dwordx4 v[12:15], v[4:5], off nt
	v_lshl_add_u64 v[4:5], v[4:5], 0, s[26:27]
	global_load_dwordx4 v[16:19], v[4:5], off nt
	v_lshl_add_u64 v[4:5], v[4:5], 0, s[26:27]
	global_load_dwordx4 v[20:23], v[4:5], off nt
	v_lshl_add_u64 v[4:5], v[4:5], 0, s[26:27]
	global_load_dwordx4 v[24:27], v[4:5], off nt
	v_lshl_add_u64 v[4:5], v[4:5], 0, s[26:27]
	global_load_dwordx4 v[28:31], v[4:5], off nt
	v_lshl_add_u64 v[4:5], v[4:5], 0, s[26:27]
	global_load_dwordx4 v[32:35], v[4:5], off nt
	v_lshl_add_u64 v[4:5], v[4:5], 0, s[26:27]
	global_load_dwordx4 v[36:39], v[4:5], off nt
	v_lshl_add_u32 v6, v3, 2, s28
	v_lshlrev_b32_e32 v6, 7, v6
	v_lshl_add_u32 v6, v2, 4, v6
	v_mov_b32_e32 v7, 0
	v_lshl_add_u64 v[6:7], s[20:21], 0, v[6:7]
	s_waitcnt vmcnt(0)
	v_cvt_pk_bf16_f32 v40, v8, v12
	v_cvt_pk_bf16_f32 v41, v16, v20
	v_cvt_pk_bf16_f32 v42, v24, v28
	v_cvt_pk_bf16_f32 v43, v32, v36
	global_store_dwordx4 v[6:7], v[40:43], off sc1
	v_cvt_pk_bf16_f32 v44, v9, v13
	v_cvt_pk_bf16_f32 v45, v17, v21
	v_cvt_pk_bf16_f32 v46, v25, v29
	v_cvt_pk_bf16_f32 v47, v33, v37
	global_store_dwordx4 v[6:7], v[44:47], off offset:128 sc1
	v_cvt_pk_bf16_f32 v48, v10, v14
	v_cvt_pk_bf16_f32 v49, v18, v22
	v_cvt_pk_bf16_f32 v50, v26, v30
	v_cvt_pk_bf16_f32 v51, v34, v38
	global_store_dwordx4 v[6:7], v[48:51], off offset:256 sc1
	v_cvt_pk_bf16_f32 v52, v11, v15
	v_cvt_pk_bf16_f32 v53, v19, v23
	v_cvt_pk_bf16_f32 v54, v27, v31
	v_cvt_pk_bf16_f32 v55, v35, v39
	global_store_dwordx4 v[6:7], v[52:55], off offset:384 sc1
.Lmy_cv6_done:
	s_branch .LBB0_780

.LBB0_785:
	v_readlane_b32 s0, v254, 0
	v_readlane_b32 s1, v254, 1
	s_cmp_gt_i32 s1, 8
	s_cselect_b64 s[0:1], -1, 0
	s_and_b64 s[4:5], s[4:5], s[0:1]
	s_andn2_b64 vcc, exec, s[4:5]
	s_cbranch_vccnz .LBB0_839
	s_waitcnt vmcnt(0)
	s_waitcnt vmcnt(0)
	s_barrier
	s_mov_b64 s[4:5], exec
	v_readlane_b32 s6, v254, 7
	v_readlane_b32 s7, v254, 8
	s_and_b64 s[6:7], s[4:5], s[6:7]
	s_mov_b64 exec, s[6:7]
	s_cbranch_execz .Lmy_cv7_entry
	s_cmpk_lg_i32 s3, 0x100
	s_cbranch_scc1 .Lmy_gb7_orig
	s_and_b32 s6, s2, 7
	s_lshl_b32 s6, s6, 6
	s_add_u32 s6, s6, 0x34200
	v_mov_b32_e32 v2, s6
	v_mov_b32_e32 v3, 1
	global_atomic_add v4, v2, v3, s[50:51] sc0
	s_movk_i32 s7, 0x4000
	s_waitcnt vmcnt(0)
	v_cmp_gt_u32_e32 vcc, 31, v4
	s_cbranch_vccz .Lmy_gb7_go

.Lmy_cv7_go:
	s_add_u32 s20, s50, s20
	s_addc_u32 s21, s51, 0
	v_and_b32_e32 v2, 7, v1
	v_lshrrev_b32_e32 v3, 3, v1
	s_lshl_b32 s24, s15, 6
	v_lshl_add_u32 v4, v2, 3, s24
	v_mul_lo_u32 v4, v4, s19
	v_lshl_add_u32 v5, v3, 2, s17
	v_add_u32_e32 v4, v4, v5
	v_mov_b32_e32 v5, 0
	v_lshlrev_b64 v[4:5], 2, v[4:5]
	s_lshl_b32 s26, s19, 2
	s_mov_b32 s27, 0
	s_lshr_b32 s28, s18, 8
	s_and_b32 s29, s18, 0xff
	s_lshl_b32 s28, s28, 5
	s_add_u32 s28, s28, s15
	s_lshl_b32 s28, s28, 8
	s_add_u32 s28, s28, s29
	s_waitcnt lgkmcnt(0)
	v_lshl_add_u64 v[4:5], s[12:13], 0, v[4:5]
	global_load_dwordx4 v[8:11], v[4:5], off nt
	v_lshl_add_u64 v[4:5], v[4:5], 0, s[26:27]
	global_load_dwordx4 v[12:15], v[4:5], off nt
	v_lshl_add_u64 v[4:5], v[4:5], 0, s[26:27]
	global_load_dwordx4 v[16:19], v[4:5], off nt
	v_lshl_add_u64 v[4:5], v[4:5], 0, s[26:27]
	global_load_dwordx4 v[20:23], v[4:5], off nt
	v_lshl_add_u64 v[4:5], v[4:5], 0, s[26:27]
	global_load_dwordx4 v[24:27], v[4:5], off nt
	v_lshl_add_u64 v[4:5], v[4:5], 0, s[26:27]
	global_load_dwordx4 v[28:31], v[4:5], off nt
	v_lshl_add_u64 v[4:5], v[4:5], 0, s[26:27]
	global_load_dwordx4 v[32:35], v[4:5], off nt
	v_lshl_add_u64 v[4:5], v[4:5], 0, s[26:27]
	global_load_dwordx4 v[36:39], v[4:5], off nt
	v_lshl_add_u32 v6, v3, 2, s28
	v_lshlrev_b32_e32 v6, 7, v6
	v_lshl_add_u32 v6, v2, 4, v6
	v_mov_b32_e32 v7, 0
	v_lshl_add_u64 v[6:7], s[20:21], 0, v[6:7]
	s_waitcnt vmcnt(0)
	v_cvt_pk_bf16_f32 v40, v8, v12
	v_cvt_pk_bf16_f32 v41, v16, v20
	v_cvt_pk_bf16_f32 v42, v24, v28
	v_cvt_pk_bf16_f32 v43, v32, v36
	global_store_dwordx4 v[6:7], v[40:43], off sc1
	v_cvt_pk_bf16_f32 v44, v9, v13
	v_cvt_pk_bf16_f32 v45, v17, v21
	v_cvt_pk_bf16_f32 v46, v25, v29
	v_cvt_pk_bf16_f32 v47, v33, v37
	global_store_dwordx4 v[6:7], v[44:47], off offset:128 sc1
	v_cvt_pk_bf16_f32 v48, v10, v14
	v_cvt_pk_bf16_f32 v49, v18, v22
	v_cvt_pk_bf16_f32 v50, v26, v30
	v_cvt_pk_bf16_f32 v51, v34, v38
	global_store_dwordx4 v[6:7], v[48:51], off offset:256 sc1
	v_cvt_pk_bf16_f32 v52, v11, v15
	v_cvt_pk_bf16_f32 v53, v19, v23
	v_cvt_pk_bf16_f32 v54, v27, v31
	v_cvt_pk_bf16_f32 v55, v35, v39
	global_store_dwordx4 v[6:7], v[52:55], off offset:384 sc1
.Lmy_cv7_done:
	s_branch .LBB0_838

.LBB0_864:
	v_readlane_b32 s0, v254, 0
	v_readlane_b32 s1, v254, 1
	s_cmp_gt_i32 s1, 9
	s_cselect_b64 s[0:1], -1, 0
	s_and_b64 s[4:5], s[4:5], s[0:1]
	s_andn2_b64 vcc, exec, s[4:5]
	s_cbranch_vccnz .LBB0_918
	s_waitcnt vmcnt(0)
	s_waitcnt vmcnt(0)
	s_barrier
	s_mov_b64 s[4:5], exec
	v_readlane_b32 s6, v254, 7
	v_readlane_b32 s7, v254, 8
	s_and_b64 s[6:7], s[4:5], s[6:7]
	s_mov_b64 exec, s[6:7]
	s_cbranch_execz .Lmy_cv8_entry
	s_cmpk_lg_i32 s3, 0x100
	s_cbranch_scc1 .Lmy_gb8_orig
	s_and_b32 s6, s2, 7
	s_lshl_b32 s6, s6, 6
	s_add_u32 s6, s6, 0x34400
	v_mov_b32_e32 v2, s6
	v_mov_b32_e32 v3, 1
	global_atomic_add v4, v2, v3, s[50:51] sc0
	s_movk_i32 s7, 0x4000
	s_waitcnt vmcnt(0)
	v_cmp_gt_u32_e32 vcc, 31, v4
	s_cbranch_vccz .Lmy_gb8_go

.LBB0_922:
	v_readlane_b32 s0, v254, 0
	v_readlane_b32 s1, v254, 1
	s_cmp_gt_i32 s1, 10
	s_cselect_b64 s[0:1], -1, 0
	s_and_b64 s[4:5], s[4:5], s[0:1]
	s_andn2_b64 vcc, exec, s[4:5]
	s_cbranch_vccnz .LBB0_976
	s_waitcnt vmcnt(0)
	s_waitcnt vmcnt(0)
	s_barrier
	s_mov_b64 s[4:5], exec
	v_readlane_b32 s6, v254, 7
	v_readlane_b32 s7, v254, 8
	s_and_b64 s[6:7], s[4:5], s[6:7]
	s_mov_b64 exec, s[6:7]
	s_cbranch_execz .LBB0_975
	s_cmpk_lg_i32 s3, 0x100
	s_cbranch_scc1 .Lmy_gb9_orig
	s_and_b32 s6, s2, 7
	s_lshl_b32 s6, s6, 6
	s_add_u32 s6, s6, 0x34600
	v_mov_b32_e32 v2, s6
	v_mov_b32_e32 v3, 1
	global_atomic_add v4, v2, v3, s[50:51] sc0
	s_movk_i32 s7, 0x4000
	s_waitcnt vmcnt(0)
	v_cmp_gt_u32_e32 vcc, 31, v4
	s_cbranch_vccz .Lmy_gb9_go

.Lmy_gb9_cspin:
	v_mov_b32_e32 v2, 0x35000
	global_load_dword v4, v2, s[50:51] offset:0 sc1
	global_load_dword v5, v2, s[50:51] offset:256 sc1
	global_load_dword v6, v2, s[50:51] offset:512 sc1
	global_load_dword v7, v2, s[50:51] offset:768 sc1
	global_load_dword v8, v2, s[50:51] offset:1024 sc1
	global_load_dword v9, v2, s[50:51] offset:1280 sc1
	global_load_dword v10, v2, s[50:51] offset:1536 sc1
	global_load_dword v11, v2, s[50:51] offset:1792 sc1
	global_load_dword v12, v2, s[50:51] offset:2048 sc1
	global_load_dword v13, v2, s[50:51] offset:2304 sc1
	global_load_dword v14, v2, s[50:51] offset:2560 sc1
	global_load_dword v15, v2, s[50:51] offset:2816 sc1
	global_load_dword v16, v2, s[50:51] offset:3072 sc1
	global_load_dword v17, v2, s[50:51] offset:3328 sc1
	global_load_dword v18, v2, s[50:51] offset:3584 sc1
	global_load_dword v19, v2, s[50:51] offset:3840 sc1
	s_waitcnt vmcnt(0)
	v_add_u32_e32 v4, v4, v5
	v_add_u32_e32 v4, v4, v6
	v_add_u32_e32 v4, v4, v7
	v_add_u32_e32 v4, v4, v8
	v_add_u32_e32 v4, v4, v9
	v_add_u32_e32 v4, v4, v10
	v_add_u32_e32 v4, v4, v11
	v_add_u32_e32 v4, v4, v12
	v_add_u32_e32 v4, v4, v13
	v_add_u32_e32 v4, v4, v14
	v_add_u32_e32 v4, v4, v15
	v_add_u32_e32 v4, v4, v16
	v_add_u32_e32 v4, v4, v17
	v_add_u32_e32 v4, v4, v18
	v_add_u32_e32 v4, v4, v19
	v_cmp_gt_u32_e32 vcc, 0x100, v4
	s_cbranch_vccz .Lmy_gb9_cgo
	s_sleep 1
	s_sub_u32 s7, s7, 1
	s_cmp_lg_u32 s7, 0
	s_cbranch_scc1 .Lmy_gb9_cspin

.LBB0_1000:
	v_readlane_b32 s0, v254, 0
	v_readlane_b32 s1, v254, 1
	s_cmp_gt_i32 s1, 11
	s_cselect_b64 s[0:1], -1, 0
	s_and_b64 s[4:5], s[4:5], s[0:1]
	s_andn2_b64 vcc, exec, s[4:5]
	s_cbranch_vccnz .LBB0_1054
	s_waitcnt vmcnt(0)
	s_waitcnt vmcnt(0)
	s_barrier
	s_mov_b64 s[4:5], exec
	v_readlane_b32 s6, v254, 7
	v_readlane_b32 s7, v254, 8
	s_and_b64 s[6:7], s[4:5], s[6:7]
	s_mov_b64 exec, s[6:7]
	s_cbranch_execz .LBB0_1053
	s_cmpk_lg_i32 s3, 0x100
	s_cbranch_scc1 .Lmy_gb10_orig
	s_and_b32 s6, s2, 7
	s_lshl_b32 s6, s6, 6
	s_add_u32 s6, s6, 0x34800
	v_mov_b32_e32 v2, s6
	v_mov_b32_e32 v3, 1
	global_atomic_add v4, v2, v3, s[50:51] sc0
	s_movk_i32 s7, 0x4000
	s_waitcnt vmcnt(0)
	v_cmp_gt_u32_e32 vcc, 31, v4
	s_cbranch_vccz .Lmy_gb10_go
